# P4 mix hook + epilogue: flat->global gate loads with counted vmcnt waits (batch i+1 in flight while batch i applied)
# baseline (speedup 1.0000x reference)
.LBB0_1030:
	s_andn2_b64 vcc, exec, s[14:15]
	s_cbranch_vccnz .LBB0_1021
	s_and_b32 s14, s62, 0x3ffffffc
	s_add_i32 s14, s58, s14
	s_ashr_i32 s15, s14, 31
	v_mov_b32_e32 v128, v224
	v_mov_b32_e32 v129, v223
	v_mov_b32_e32 v130, v226
	s_lshl_b64 s[14:15], s[14:15], 17
	s_add_u32 s14, s30, s14
	v_lshlrev_b32_e32 v227, 3, v128
	s_addc_u32 s15, s31, s15
	v_add_u32_e32 v192, s38, v227
	v_lshl_add_u64 v[128:129], v[192:193], 1, s[14:15]
	global_load_dwordx4 v[184:187], v[128:129], off
	v_add_co_u32_e32 v128, vcc, s75, v128
	v_add_u32_e32 v192, s39, v227
	s_nop 0
	v_addc_co_u32_e32 v129, vcc, 0, v129, vcc
	global_load_dwordx4 v[188:191], v[128:129], off
	v_lshl_add_u64 v[128:129], v[192:193], 1, s[14:15]
	global_load_dwordx4 v[180:183], v[128:129], off
	v_add_co_u32_e32 v128, vcc, s75, v128
	v_add_u32_e32 v192, s40, v227
	s_nop 0
	v_addc_co_u32_e32 v129, vcc, 0, v129, vcc
	global_load_dwordx4 v[176:179], v[128:129], off
	v_lshl_add_u64 v[128:129], v[192:193], 1, s[14:15]
	global_load_dwordx4 v[172:175], v[128:129], off
	v_add_co_u32_e32 v128, vcc, s75, v128
	v_add_u32_e32 v192, s42, v227
	s_nop 0
	v_addc_co_u32_e32 v129, vcc, 0, v129, vcc
	global_load_dwordx4 v[168:171], v[128:129], off
	v_lshl_add_u64 v[128:129], v[192:193], 1, s[14:15]
	global_load_dwordx4 v[156:159], v[128:129], off
	v_add_co_u32_e32 v128, vcc, s75, v128
	v_add_u32_e32 v192, s43, v227
	s_nop 0
	v_addc_co_u32_e32 v129, vcc, 0, v129, vcc
	global_load_dwordx4 v[152:155], v[128:129], off
	v_lshl_add_u64 v[128:129], v[192:193], 1, s[14:15]
	global_load_dwordx4 v[164:167], v[128:129], off
	v_add_co_u32_e32 v128, vcc, s75, v128
	v_add_u32_e32 v192, s44, v227
	s_nop 0
	v_addc_co_u32_e32 v129, vcc, 0, v129, vcc
	global_load_dwordx4 v[160:163], v[128:129], off
	v_lshl_add_u64 v[128:129], v[192:193], 1, s[14:15]
	global_load_dwordx4 v[148:151], v[128:129], off
	v_add_co_u32_e32 v128, vcc, s75, v128
	v_add_u32_e32 v192, s45, v227
	s_nop 0
	v_addc_co_u32_e32 v129, vcc, 0, v129, vcc
	global_load_dwordx4 v[144:147], v[128:129], off
	v_lshl_add_u64 v[128:129], v[192:193], 1, s[14:15]
	v_add_u32_e32 v192, s46, v227
	v_lshl_add_u64 v[136:137], v[192:193], 1, s[14:15]
	global_load_dwordx4 v[140:143], v[128:129], off
	v_add_co_u32_e32 v128, vcc, s75, v128
	s_waitcnt vmcnt(12)
	v_lshlrev_b32_e32 v192, 16, v184
	v_and_b32_e32 v184, 0xffff0000, v184
	v_rcp_f32_e32 v229, v184
	v_lshlrev_b32_e32 v184, 16, v185
	v_and_b32_e32 v185, 0xffff0000, v185
	v_rcp_f32_e32 v184, v184
	v_rcp_f32_e32 v185, v185
	s_waitcnt vmcnt(11)
	v_lshlrev_b32_e32 v230, 16, v188
	v_and_b32_e32 v231, 0xffff0000, v188
	v_lshlrev_b32_e32 v188, 16, v189
	v_and_b32_e32 v189, 0xffff0000, v189
	v_pk_mul_f32 v[184:185], v[184:185], v[188:189]
	v_lshlrev_b32_e32 v188, 16, v190
	v_pk_mul_f32 v[126:127], v[126:127], v[184:185]
	v_lshlrev_b32_e32 v184, 16, v186
	v_and_b32_e32 v185, 0xffff0000, v186
	v_rcp_f32_e32 v184, v184
	v_rcp_f32_e32 v185, v185
	v_and_b32_e32 v189, 0xffff0000, v190
	v_lshlrev_b32_e32 v186, 16, v191
	v_addc_co_u32_e32 v129, vcc, 0, v129, vcc
	v_pk_mul_f32 v[184:185], v[184:185], v[188:189]
	global_load_dwordx4 v[132:135], v[128:129], off
	v_pk_mul_f32 v[120:121], v[120:121], v[184:185]
	v_lshlrev_b32_e32 v184, 16, v187
	v_and_b32_e32 v185, 0xffff0000, v187
	v_rcp_f32_e32 v184, v184
	v_rcp_f32_e32 v185, v185
	v_and_b32_e32 v187, 0xffff0000, v191
	global_load_dwordx4 v[128:131], v[136:137], off
	v_add_co_u32_e32 v136, vcc, s75, v136
	v_pk_mul_f32 v[184:185], v[184:185], v[186:187]
	s_waitcnt vmcnt(11)
	v_lshlrev_b32_e32 v186, 16, v176
	v_pk_mul_f32 v[122:123], v[122:123], v[184:185]
	v_lshlrev_b32_e32 v184, 16, v180
	v_and_b32_e32 v180, 0xffff0000, v180
	v_and_b32_e32 v187, 0xffff0000, v176
	v_lshlrev_b32_e32 v176, 16, v181
	v_rcp_f32_e32 v185, v180
	v_rcp_f32_e32 v180, v176
	v_and_b32_e32 v176, 0xffff0000, v181
	v_rcp_f32_e32 v181, v176
	v_lshlrev_b32_e32 v176, 16, v177
	v_and_b32_e32 v177, 0xffff0000, v177
	v_addc_co_u32_e32 v137, vcc, 0, v137, vcc
	v_pk_mul_f32 v[176:177], v[180:181], v[176:177]
	v_lshlrev_b32_e32 v180, 16, v178
	v_pk_mul_f32 v[118:119], v[118:119], v[176:177]
	v_lshlrev_b32_e32 v176, 16, v182
	v_and_b32_e32 v177, 0xffff0000, v182
	v_rcp_f32_e32 v176, v176
	v_rcp_f32_e32 v177, v177
	v_and_b32_e32 v181, 0xffff0000, v178
	v_lshlrev_b32_e32 v178, 16, v179
	v_and_b32_e32 v179, 0xffff0000, v179
	v_pk_mul_f32 v[176:177], v[176:177], v[180:181]
	global_load_dwordx4 v[136:139], v[136:137], off
	v_pk_mul_f32 v[112:113], v[112:113], v[176:177]
	v_lshlrev_b32_e32 v176, 16, v183
	v_and_b32_e32 v177, 0xffff0000, v183
	v_rcp_f32_e32 v176, v176
	v_rcp_f32_e32 v177, v177
	v_rcp_f32_e32 v184, v184
	v_rcp_f32_e32 v228, v192
	v_pk_mul_f32 v[176:177], v[176:177], v[178:179]
	s_waitcnt vmcnt(10)
	v_lshlrev_b32_e32 v178, 16, v168
	v_pk_mul_f32 v[114:115], v[114:115], v[176:177]
	v_lshlrev_b32_e32 v176, 16, v172
	v_and_b32_e32 v172, 0xffff0000, v172
	v_and_b32_e32 v179, 0xffff0000, v168
	v_lshlrev_b32_e32 v168, 16, v173
	v_rcp_f32_e32 v177, v172
	v_rcp_f32_e32 v172, v168
	v_and_b32_e32 v168, 0xffff0000, v173
	v_rcp_f32_e32 v173, v168
	v_lshlrev_b32_e32 v168, 16, v169
	v_and_b32_e32 v169, 0xffff0000, v169
	v_rcp_f32_e32 v176, v176
	v_pk_mul_f32 v[168:169], v[172:173], v[168:169]
	v_lshlrev_b32_e32 v172, 16, v170
	v_pk_mul_f32 v[110:111], v[110:111], v[168:169]
	v_lshlrev_b32_e32 v168, 16, v174
	v_and_b32_e32 v169, 0xffff0000, v174
	v_rcp_f32_e32 v168, v168
	v_rcp_f32_e32 v169, v169
	v_and_b32_e32 v173, 0xffff0000, v170
	v_lshlrev_b32_e32 v170, 16, v171
	v_and_b32_e32 v171, 0xffff0000, v171
	v_pk_mul_f32 v[168:169], v[168:169], v[172:173]
	v_pk_mul_f32 v[184:185], v[184:185], v[186:187]
	v_pk_mul_f32 v[104:105], v[104:105], v[168:169]
	v_lshlrev_b32_e32 v168, 16, v175
	v_and_b32_e32 v169, 0xffff0000, v175
	v_rcp_f32_e32 v168, v168
	v_rcp_f32_e32 v169, v169
	v_pk_mul_f32 v[116:117], v[116:117], v[184:185]
	v_pk_mul_f32 v[176:177], v[176:177], v[178:179]
	v_pk_mul_f32 v[228:229], v[228:229], v[230:231]
	v_pk_mul_f32 v[168:169], v[168:169], v[170:171]
	s_waitcnt vmcnt(8)
	v_lshlrev_b32_e32 v170, 16, v152
	v_pk_mul_f32 v[106:107], v[106:107], v[168:169]
	v_lshlrev_b32_e32 v168, 16, v156
	v_and_b32_e32 v156, 0xffff0000, v156
	v_and_b32_e32 v171, 0xffff0000, v152
	v_lshlrev_b32_e32 v152, 16, v157
	v_rcp_f32_e32 v169, v156
	v_rcp_f32_e32 v156, v152
	v_and_b32_e32 v152, 0xffff0000, v157
	v_rcp_f32_e32 v157, v152
	v_lshlrev_b32_e32 v152, 16, v153
	v_and_b32_e32 v153, 0xffff0000, v153
	v_rcp_f32_e32 v168, v168
	v_pk_mul_f32 v[152:153], v[156:157], v[152:153]
	v_lshlrev_b32_e32 v156, 16, v154
	v_pk_mul_f32 v[102:103], v[102:103], v[152:153]
	v_lshlrev_b32_e32 v152, 16, v158
	v_and_b32_e32 v153, 0xffff0000, v158
	v_rcp_f32_e32 v152, v152
	v_rcp_f32_e32 v153, v153
	v_and_b32_e32 v157, 0xffff0000, v154
	v_lshlrev_b32_e32 v154, 16, v155
	v_and_b32_e32 v155, 0xffff0000, v155
	v_pk_mul_f32 v[152:153], v[152:153], v[156:157]
	v_pk_mul_f32 v[108:109], v[108:109], v[176:177]
	v_pk_mul_f32 v[96:97], v[96:97], v[152:153]
	v_lshlrev_b32_e32 v152, 16, v159
	v_and_b32_e32 v153, 0xffff0000, v159
	v_rcp_f32_e32 v152, v152
	v_rcp_f32_e32 v153, v153
	v_pk_mul_f32 v[168:169], v[168:169], v[170:171]
	s_waitcnt vmcnt(6)
	v_lshlrev_b32_e32 v230, 16, v160
	v_pk_mul_f32 v[100:101], v[100:101], v[168:169]
	v_pk_mul_f32 v[152:153], v[152:153], v[154:155]
	v_add_u32_e32 v154, 0x1000, v227
	v_add_u32_e32 v192, s38, v154
	v_pk_mul_f32 v[98:99], v[98:99], v[152:153]
	v_lshl_add_u64 v[152:153], v[192:193], 1, s[14:15]
	global_load_dwordx4 v[184:187], v[152:153], off
	v_add_co_u32_e32 v152, vcc, s75, v152
	v_add_u32_e32 v192, s39, v154
	s_nop 0
	v_addc_co_u32_e32 v153, vcc, 0, v153, vcc
	global_load_dwordx4 v[188:191], v[152:153], off
	v_lshl_add_u64 v[152:153], v[192:193], 1, s[14:15]
	global_load_dwordx4 v[176:179], v[152:153], off
	v_add_co_u32_e32 v152, vcc, s75, v152
	v_add_u32_e32 v192, s40, v154
	s_nop 0
	v_addc_co_u32_e32 v153, vcc, 0, v153, vcc
	global_load_dwordx4 v[180:183], v[152:153], off
	v_lshl_add_u64 v[152:153], v[192:193], 1, s[14:15]
	global_load_dwordx4 v[168:171], v[152:153], off
	v_add_co_u32_e32 v152, vcc, s75, v152
	v_add_u32_e32 v192, s42, v154
	s_nop 0
	v_addc_co_u32_e32 v153, vcc, 0, v153, vcc
	global_load_dwordx4 v[172:175], v[152:153], off
	v_lshl_add_u64 v[152:153], v[192:193], 1, s[14:15]
	v_lshlrev_b32_e32 v192, 16, v164
	v_and_b32_e32 v164, 0xffff0000, v164
	v_and_b32_e32 v231, 0xffff0000, v160
	v_lshlrev_b32_e32 v160, 16, v165
	v_pk_mul_f32 v[124:125], v[124:125], v[228:229]
	v_rcp_f32_e32 v229, v164
	v_rcp_f32_e32 v164, v160
	v_and_b32_e32 v160, 0xffff0000, v165
	v_rcp_f32_e32 v165, v160
	v_lshlrev_b32_e32 v160, 16, v161
	v_and_b32_e32 v161, 0xffff0000, v161
	global_load_dwordx4 v[156:159], v[152:153], off
	v_pk_mul_f32 v[160:161], v[164:165], v[160:161]
	v_lshlrev_b32_e32 v164, 16, v162
	v_pk_mul_f32 v[94:95], v[94:95], v[160:161]
	v_lshlrev_b32_e32 v160, 16, v166
	v_and_b32_e32 v161, 0xffff0000, v166
	v_rcp_f32_e32 v160, v160
	v_rcp_f32_e32 v161, v161
	v_and_b32_e32 v165, 0xffff0000, v162
	v_lshlrev_b32_e32 v162, 16, v163
	v_and_b32_e32 v163, 0xffff0000, v163
	v_pk_mul_f32 v[160:161], v[160:161], v[164:165]
	v_add_co_u32_e32 v152, vcc, s75, v152
	v_pk_mul_f32 v[88:89], v[88:89], v[160:161]
	v_lshlrev_b32_e32 v160, 16, v167
	v_and_b32_e32 v161, 0xffff0000, v167
	v_rcp_f32_e32 v160, v160
	v_rcp_f32_e32 v161, v161
	v_addc_co_u32_e32 v153, vcc, 0, v153, vcc
	global_load_dwordx4 v[152:155], v[152:153], off
	v_pk_mul_f32 v[160:161], v[160:161], v[162:163]
	s_waitcnt vmcnt(12)
	v_lshlrev_b32_e32 v162, 16, v144
	v_pk_mul_f32 v[90:91], v[90:91], v[160:161]
	v_lshlrev_b32_e32 v160, 16, v148
	v_and_b32_e32 v148, 0xffff0000, v148
	v_and_b32_e32 v163, 0xffff0000, v144
	v_lshlrev_b32_e32 v144, 16, v149
	v_rcp_f32_e32 v161, v148
	v_rcp_f32_e32 v148, v144
	v_and_b32_e32 v144, 0xffff0000, v149
	v_rcp_f32_e32 v149, v144
	v_lshlrev_b32_e32 v144, 16, v145
	v_and_b32_e32 v145, 0xffff0000, v145
	v_rcp_f32_e32 v160, v160
	v_pk_mul_f32 v[144:145], v[148:149], v[144:145]
	v_lshlrev_b32_e32 v148, 16, v146
	v_pk_mul_f32 v[86:87], v[86:87], v[144:145]
	v_lshlrev_b32_e32 v144, 16, v150
	v_and_b32_e32 v145, 0xffff0000, v150
	v_rcp_f32_e32 v144, v144
	v_rcp_f32_e32 v145, v145
	v_and_b32_e32 v149, 0xffff0000, v146
	v_lshlrev_b32_e32 v146, 16, v147
	v_and_b32_e32 v147, 0xffff0000, v147
	v_pk_mul_f32 v[144:145], v[144:145], v[148:149]
	v_rcp_f32_e32 v228, v192
	v_pk_mul_f32 v[80:81], v[80:81], v[144:145]
	v_lshlrev_b32_e32 v144, 16, v151
	v_and_b32_e32 v145, 0xffff0000, v151
	v_rcp_f32_e32 v144, v144
	v_rcp_f32_e32 v145, v145
	v_pk_mul_f32 v[160:161], v[160:161], v[162:163]
	v_pk_mul_f32 v[228:229], v[228:229], v[230:231]
	v_pk_mul_f32 v[144:145], v[144:145], v[146:147]
	s_waitcnt vmcnt(10)
	v_lshlrev_b32_e32 v146, 16, v132
	v_pk_mul_f32 v[82:83], v[82:83], v[144:145]
	v_lshlrev_b32_e32 v144, 16, v140
	v_and_b32_e32 v140, 0xffff0000, v140
	v_and_b32_e32 v147, 0xffff0000, v132
	v_lshlrev_b32_e32 v132, 16, v141
	v_rcp_f32_e32 v145, v140
	v_rcp_f32_e32 v140, v132
	v_and_b32_e32 v132, 0xffff0000, v141
	v_rcp_f32_e32 v141, v132
	v_lshlrev_b32_e32 v132, 16, v133
	v_and_b32_e32 v133, 0xffff0000, v133
	v_rcp_f32_e32 v144, v144
	v_pk_mul_f32 v[132:133], v[140:141], v[132:133]
	v_lshlrev_b32_e32 v140, 16, v134
	v_pk_mul_f32 v[78:79], v[78:79], v[132:133]
	v_lshlrev_b32_e32 v132, 16, v142
	v_and_b32_e32 v133, 0xffff0000, v142
	v_rcp_f32_e32 v132, v132
	v_rcp_f32_e32 v133, v133
	v_and_b32_e32 v141, 0xffff0000, v134
	v_lshlrev_b32_e32 v134, 16, v135
	v_and_b32_e32 v135, 0xffff0000, v135
	v_pk_mul_f32 v[132:133], v[132:133], v[140:141]
	v_pk_mul_f32 v[84:85], v[84:85], v[160:161]
	v_pk_mul_f32 v[72:73], v[72:73], v[132:133]
	v_lshlrev_b32_e32 v132, 16, v143
	v_and_b32_e32 v133, 0xffff0000, v143
	v_rcp_f32_e32 v132, v132
	v_rcp_f32_e32 v133, v133
	v_pk_mul_f32 v[144:145], v[144:145], v[146:147]
	v_pk_mul_f32 v[92:93], v[92:93], v[228:229]
	v_pk_mul_f32 v[76:77], v[76:77], v[144:145]
	v_pk_mul_f32 v[132:133], v[132:133], v[134:135]
	s_waitcnt vmcnt(8)
	v_lshlrev_b32_e32 v134, 16, v136
	v_pk_mul_f32 v[74:75], v[74:75], v[132:133]
	v_lshlrev_b32_e32 v132, 16, v128
	v_and_b32_e32 v128, 0xffff0000, v128
	v_rcp_f32_e32 v132, v132
	v_rcp_f32_e32 v133, v128
	v_lshlrev_b32_e32 v128, 16, v129
	v_and_b32_e32 v129, 0xffff0000, v129
	v_rcp_f32_e32 v128, v128
	v_rcp_f32_e32 v129, v129
	v_and_b32_e32 v135, 0xffff0000, v136
	v_pk_mul_f32 v[132:133], v[132:133], v[134:135]
	s_waitcnt vmcnt(6)
	v_lshlrev_b32_e32 v230, 16, v188
	v_pk_mul_f32 v[68:69], v[68:69], v[132:133]
	v_lshlrev_b32_e32 v132, 16, v137
	v_and_b32_e32 v133, 0xffff0000, v137
	v_pk_mul_f32 v[128:129], v[128:129], v[132:133]
	v_lshlrev_b32_e32 v132, 16, v138
	v_pk_mul_f32 v[70:71], v[70:71], v[128:129]
	v_lshlrev_b32_e32 v128, 16, v130
	v_and_b32_e32 v129, 0xffff0000, v130
	v_rcp_f32_e32 v128, v128
	v_rcp_f32_e32 v129, v129
	v_and_b32_e32 v133, 0xffff0000, v138
	v_lshlrev_b32_e32 v130, 16, v139
	v_and_b32_e32 v231, 0xffff0000, v188
	v_pk_mul_f32 v[128:129], v[128:129], v[132:133]
	v_lshlrev_b32_e32 v188, 16, v189
	v_pk_mul_f32 v[64:65], v[64:65], v[128:129]
	v_lshlrev_b32_e32 v128, 16, v131
	v_and_b32_e32 v129, 0xffff0000, v131
	v_rcp_f32_e32 v128, v128
	v_rcp_f32_e32 v129, v129
	v_and_b32_e32 v131, 0xffff0000, v139
	v_and_b32_e32 v189, 0xffff0000, v189
	v_pk_mul_f32 v[128:129], v[128:129], v[130:131]
	v_add_u32_e32 v130, 0x1800, v227
	v_add_u32_e32 v192, s38, v130
	v_pk_mul_f32 v[66:67], v[66:67], v[128:129]
	v_lshl_add_u64 v[128:129], v[192:193], 1, s[14:15]
	global_load_dwordx4 v[160:163], v[128:129], off
	v_add_co_u32_e32 v128, vcc, s75, v128
	v_add_u32_e32 v192, s39, v130
	s_nop 0
	v_addc_co_u32_e32 v129, vcc, 0, v129, vcc
	global_load_dwordx4 v[164:167], v[128:129], off
	v_lshl_add_u64 v[128:129], v[192:193], 1, s[14:15]
	global_load_dwordx4 v[144:147], v[128:129], off
	v_add_co_u32_e32 v128, vcc, s75, v128
	v_add_u32_e32 v192, s40, v130
	s_nop 0
	v_addc_co_u32_e32 v129, vcc, 0, v129, vcc
	global_load_dwordx4 v[148:151], v[128:129], off
	v_lshl_add_u64 v[128:129], v[192:193], 1, s[14:15]
	global_load_dwordx4 v[136:139], v[128:129], off
	v_add_co_u32_e32 v128, vcc, s75, v128
	v_add_u32_e32 v192, s42, v130
	s_nop 0
	v_addc_co_u32_e32 v129, vcc, 0, v129, vcc
	global_load_dwordx4 v[140:143], v[128:129], off
	v_lshl_add_u64 v[128:129], v[192:193], 1, s[14:15]
	v_lshlrev_b32_e32 v192, 16, v184
	v_and_b32_e32 v184, 0xffff0000, v184
	v_rcp_f32_e32 v229, v184
	v_lshlrev_b32_e32 v184, 16, v185
	v_and_b32_e32 v185, 0xffff0000, v185
	v_rcp_f32_e32 v184, v184
	v_rcp_f32_e32 v185, v185
	global_load_dwordx4 v[132:135], v[128:129], off
	v_add_co_u32_e32 v128, vcc, s75, v128
	v_pk_mul_f32 v[184:185], v[184:185], v[188:189]
	v_lshlrev_b32_e32 v188, 16, v190
	v_pk_mul_f32 v[62:63], v[62:63], v[184:185]
	v_lshlrev_b32_e32 v184, 16, v186
	v_and_b32_e32 v185, 0xffff0000, v186
	v_rcp_f32_e32 v184, v184
	v_rcp_f32_e32 v185, v185
	v_and_b32_e32 v189, 0xffff0000, v190
	v_lshlrev_b32_e32 v186, 16, v191
	v_addc_co_u32_e32 v129, vcc, 0, v129, vcc
	v_pk_mul_f32 v[184:185], v[184:185], v[188:189]
	global_load_dwordx4 v[128:131], v[128:129], off
	v_pk_mul_f32 v[56:57], v[56:57], v[184:185]
	v_lshlrev_b32_e32 v184, 16, v187
	v_and_b32_e32 v185, 0xffff0000, v187
	v_rcp_f32_e32 v184, v184
	v_rcp_f32_e32 v185, v185
	v_and_b32_e32 v187, 0xffff0000, v191
	v_rcp_f32_e32 v228, v192
	v_pk_mul_f32 v[184:185], v[184:185], v[186:187]
	s_waitcnt vmcnt(12)
	v_lshlrev_b32_e32 v186, 16, v180
	v_pk_mul_f32 v[58:59], v[58:59], v[184:185]
	v_lshlrev_b32_e32 v184, 16, v176
	v_and_b32_e32 v176, 0xffff0000, v176
	v_rcp_f32_e32 v185, v176
	v_lshlrev_b32_e32 v176, 16, v177
	v_and_b32_e32 v177, 0xffff0000, v177
	v_rcp_f32_e32 v176, v176
	v_rcp_f32_e32 v177, v177
	v_and_b32_e32 v187, 0xffff0000, v180
	v_lshlrev_b32_e32 v180, 16, v181
	v_and_b32_e32 v181, 0xffff0000, v181
	v_pk_mul_f32 v[176:177], v[176:177], v[180:181]
	v_lshlrev_b32_e32 v180, 16, v182
	v_pk_mul_f32 v[54:55], v[54:55], v[176:177]
	v_lshlrev_b32_e32 v176, 16, v178
	v_and_b32_e32 v177, 0xffff0000, v178
	v_rcp_f32_e32 v176, v176
	v_rcp_f32_e32 v177, v177
	v_and_b32_e32 v181, 0xffff0000, v182
	v_lshlrev_b32_e32 v178, 16, v183
	v_rcp_f32_e32 v184, v184
	v_pk_mul_f32 v[176:177], v[176:177], v[180:181]
	v_pk_mul_f32 v[228:229], v[228:229], v[230:231]
	v_pk_mul_f32 v[48:49], v[48:49], v[176:177]
	v_lshlrev_b32_e32 v176, 16, v179
	v_and_b32_e32 v177, 0xffff0000, v179
	v_rcp_f32_e32 v176, v176
	v_rcp_f32_e32 v177, v177
	v_and_b32_e32 v179, 0xffff0000, v183
	v_pk_mul_f32 v[184:185], v[184:185], v[186:187]
	v_pk_mul_f32 v[60:61], v[60:61], v[228:229]
	v_pk_mul_f32 v[176:177], v[176:177], v[178:179]
	s_waitcnt vmcnt(10)
	v_lshlrev_b32_e32 v178, 16, v172
	v_pk_mul_f32 v[50:51], v[50:51], v[176:177]
	v_lshlrev_b32_e32 v176, 16, v168
	v_and_b32_e32 v168, 0xffff0000, v168
	v_rcp_f32_e32 v177, v168
	v_lshlrev_b32_e32 v168, 16, v169
	v_and_b32_e32 v169, 0xffff0000, v169
	v_rcp_f32_e32 v168, v168
	v_rcp_f32_e32 v169, v169
	v_and_b32_e32 v179, 0xffff0000, v172
	v_lshlrev_b32_e32 v172, 16, v173
	v_and_b32_e32 v173, 0xffff0000, v173
	v_pk_mul_f32 v[168:169], v[168:169], v[172:173]
	v_lshlrev_b32_e32 v172, 16, v174
	v_pk_mul_f32 v[46:47], v[46:47], v[168:169]
	v_lshlrev_b32_e32 v168, 16, v170
	v_and_b32_e32 v169, 0xffff0000, v170
	v_rcp_f32_e32 v168, v168
	v_rcp_f32_e32 v169, v169
	v_and_b32_e32 v173, 0xffff0000, v174
	v_lshlrev_b32_e32 v170, 16, v175
	v_rcp_f32_e32 v176, v176
	v_pk_mul_f32 v[168:169], v[168:169], v[172:173]
	v_pk_mul_f32 v[52:53], v[52:53], v[184:185]
	v_pk_mul_f32 v[40:41], v[40:41], v[168:169]
	v_lshlrev_b32_e32 v168, 16, v171
	v_and_b32_e32 v169, 0xffff0000, v171
	v_rcp_f32_e32 v168, v168
	v_rcp_f32_e32 v169, v169
	v_and_b32_e32 v171, 0xffff0000, v175
	v_pk_mul_f32 v[176:177], v[176:177], v[178:179]
	v_pk_mul_f32 v[168:169], v[168:169], v[170:171]
	s_nop 0
	v_pk_mul_f32 v[42:43], v[42:43], v[168:169]
	s_waitcnt vmcnt(9)
	v_lshlrev_b32_e32 v168, 16, v156
	v_and_b32_e32 v156, 0xffff0000, v156
	s_waitcnt vmcnt(8)
	v_lshlrev_b32_e32 v170, 16, v152
	v_and_b32_e32 v171, 0xffff0000, v152
	v_lshlrev_b32_e32 v152, 16, v157
	v_rcp_f32_e32 v169, v156
	v_rcp_f32_e32 v156, v152
	v_and_b32_e32 v152, 0xffff0000, v157
	v_rcp_f32_e32 v157, v152
	v_lshlrev_b32_e32 v152, 16, v153
	v_and_b32_e32 v153, 0xffff0000, v153
	v_rcp_f32_e32 v168, v168
	v_pk_mul_f32 v[152:153], v[156:157], v[152:153]
	v_lshlrev_b32_e32 v156, 16, v154
	v_pk_mul_f32 v[38:39], v[38:39], v[152:153]
	v_lshlrev_b32_e32 v152, 16, v158
	v_and_b32_e32 v153, 0xffff0000, v158
	v_rcp_f32_e32 v152, v152
	v_rcp_f32_e32 v153, v153
	v_and_b32_e32 v157, 0xffff0000, v154
	v_lshlrev_b32_e32 v154, 16, v155
	v_and_b32_e32 v155, 0xffff0000, v155
	v_pk_mul_f32 v[152:153], v[152:153], v[156:157]
	v_pk_mul_f32 v[168:169], v[168:169], v[170:171]
	v_pk_mul_f32 v[32:33], v[32:33], v[152:153]
	v_lshlrev_b32_e32 v152, 16, v159
	v_and_b32_e32 v153, 0xffff0000, v159
	v_rcp_f32_e32 v152, v152
	v_rcp_f32_e32 v153, v153
	v_pk_mul_f32 v[44:45], v[44:45], v[176:177]
	v_pk_mul_f32 v[36:37], v[36:37], v[168:169]
	v_pk_mul_f32 v[152:153], v[152:153], v[154:155]
	s_nop 0
	v_pk_mul_f32 v[34:35], v[34:35], v[152:153]
	s_waitcnt vmcnt(7)
	v_lshlrev_b32_e32 v152, 16, v160
	v_and_b32_e32 v153, 0xffff0000, v160
	v_rcp_f32_e32 v152, v152
	v_rcp_f32_e32 v153, v153
	s_waitcnt vmcnt(6)
	v_lshlrev_b32_e32 v154, 16, v164
	v_and_b32_e32 v155, 0xffff0000, v164
	v_pk_mul_f32 v[152:153], v[152:153], v[154:155]
	s_nop 0
	v_pk_mul_f32 v[28:29], v[28:29], v[152:153]
	v_lshlrev_b32_e32 v152, 16, v161
	v_and_b32_e32 v153, 0xffff0000, v161
	v_rcp_f32_e32 v152, v152
	v_rcp_f32_e32 v153, v153
	v_lshlrev_b32_e32 v154, 16, v165
	v_and_b32_e32 v155, 0xffff0000, v165
	v_pk_mul_f32 v[152:153], v[152:153], v[154:155]
	s_nop 0
	v_pk_mul_f32 v[30:31], v[30:31], v[152:153]
	v_lshlrev_b32_e32 v152, 16, v162
	v_and_b32_e32 v153, 0xffff0000, v162
	v_rcp_f32_e32 v152, v152
	v_rcp_f32_e32 v153, v153
	v_lshlrev_b32_e32 v154, 16, v166
	v_and_b32_e32 v155, 0xffff0000, v166
	v_pk_mul_f32 v[152:153], v[152:153], v[154:155]
	s_nop 0
	v_pk_mul_f32 v[24:25], v[24:25], v[152:153]
	v_lshlrev_b32_e32 v152, 16, v163
	v_and_b32_e32 v153, 0xffff0000, v163
	v_rcp_f32_e32 v152, v152
	v_rcp_f32_e32 v153, v153
	v_lshlrev_b32_e32 v154, 16, v167
	v_and_b32_e32 v155, 0xffff0000, v167
	v_pk_mul_f32 v[152:153], v[152:153], v[154:155]
	s_nop 0
	v_pk_mul_f32 v[26:27], v[26:27], v[152:153]
	s_waitcnt vmcnt(5)
	v_lshlrev_b32_e32 v152, 16, v144
	v_and_b32_e32 v144, 0xffff0000, v144
	v_rcp_f32_e32 v153, v144
	v_lshlrev_b32_e32 v144, 16, v145
	v_and_b32_e32 v145, 0xffff0000, v145
	v_rcp_f32_e32 v144, v144
	v_rcp_f32_e32 v145, v145
	s_waitcnt vmcnt(4)
	v_lshlrev_b32_e32 v154, 16, v148
	v_and_b32_e32 v155, 0xffff0000, v148
	v_lshlrev_b32_e32 v148, 16, v149
	v_and_b32_e32 v149, 0xffff0000, v149
	v_pk_mul_f32 v[144:145], v[144:145], v[148:149]
	v_lshlrev_b32_e32 v148, 16, v150
	v_pk_mul_f32 v[22:23], v[22:23], v[144:145]
	v_lshlrev_b32_e32 v144, 16, v146
	v_and_b32_e32 v145, 0xffff0000, v146
	v_rcp_f32_e32 v144, v144
	v_rcp_f32_e32 v145, v145
	v_and_b32_e32 v149, 0xffff0000, v150
	v_lshlrev_b32_e32 v146, 16, v151
	v_rcp_f32_e32 v152, v152
	v_pk_mul_f32 v[144:145], v[144:145], v[148:149]
	v_pk_mul_f32 v[152:153], v[152:153], v[154:155]
	v_pk_mul_f32 v[16:17], v[16:17], v[144:145]
	v_lshlrev_b32_e32 v144, 16, v147
	v_and_b32_e32 v145, 0xffff0000, v147
	v_rcp_f32_e32 v144, v144
	v_rcp_f32_e32 v145, v145
	v_and_b32_e32 v147, 0xffff0000, v151
	v_pk_mul_f32 v[20:21], v[20:21], v[152:153]
	v_pk_mul_f32 v[144:145], v[144:145], v[146:147]
	s_nop 0
	v_pk_mul_f32 v[18:19], v[18:19], v[144:145]
	s_waitcnt vmcnt(3)
	v_lshlrev_b32_e32 v144, 16, v136
	v_and_b32_e32 v136, 0xffff0000, v136
	v_rcp_f32_e32 v145, v136
	v_lshlrev_b32_e32 v136, 16, v137
	v_and_b32_e32 v137, 0xffff0000, v137
	v_rcp_f32_e32 v136, v136
	v_rcp_f32_e32 v137, v137
	s_waitcnt vmcnt(2)
	v_lshlrev_b32_e32 v146, 16, v140
	v_and_b32_e32 v147, 0xffff0000, v140
	v_lshlrev_b32_e32 v140, 16, v141
	v_and_b32_e32 v141, 0xffff0000, v141
	v_pk_mul_f32 v[136:137], v[136:137], v[140:141]
	v_lshlrev_b32_e32 v140, 16, v142
	v_pk_mul_f32 v[14:15], v[14:15], v[136:137]
	v_lshlrev_b32_e32 v136, 16, v138
	v_and_b32_e32 v137, 0xffff0000, v138
	v_rcp_f32_e32 v136, v136
	v_rcp_f32_e32 v137, v137
	v_and_b32_e32 v141, 0xffff0000, v142
	v_lshlrev_b32_e32 v138, 16, v143
	v_rcp_f32_e32 v144, v144
	v_pk_mul_f32 v[136:137], v[136:137], v[140:141]
	v_pk_mul_f32 v[144:145], v[144:145], v[146:147]
	v_pk_mul_f32 v[8:9], v[8:9], v[136:137]
	v_lshlrev_b32_e32 v136, 16, v139
	v_and_b32_e32 v137, 0xffff0000, v139
	v_rcp_f32_e32 v136, v136
	v_rcp_f32_e32 v137, v137
	v_and_b32_e32 v139, 0xffff0000, v143
	v_pk_mul_f32 v[12:13], v[12:13], v[144:145]
	v_pk_mul_f32 v[136:137], v[136:137], v[138:139]
	s_nop 0
	v_pk_mul_f32 v[10:11], v[10:11], v[136:137]
	s_waitcnt vmcnt(1)
	v_lshlrev_b32_e32 v136, 16, v132
	v_and_b32_e32 v132, 0xffff0000, v132
	s_waitcnt vmcnt(0)
	v_lshlrev_b32_e32 v138, 16, v128
	v_and_b32_e32 v139, 0xffff0000, v128
	v_lshlrev_b32_e32 v128, 16, v133
	v_rcp_f32_e32 v137, v132
	v_rcp_f32_e32 v132, v128
	v_and_b32_e32 v128, 0xffff0000, v133
	v_rcp_f32_e32 v133, v128
	v_lshlrev_b32_e32 v128, 16, v129
	v_and_b32_e32 v129, 0xffff0000, v129
	v_rcp_f32_e32 v136, v136
	v_pk_mul_f32 v[128:129], v[132:133], v[128:129]
	v_lshlrev_b32_e32 v132, 16, v130
	v_pk_mul_f32 v[6:7], v[6:7], v[128:129]
	v_lshlrev_b32_e32 v128, 16, v134
	v_and_b32_e32 v129, 0xffff0000, v134
	v_rcp_f32_e32 v128, v128
	v_rcp_f32_e32 v129, v129
	v_and_b32_e32 v133, 0xffff0000, v130
	v_lshlrev_b32_e32 v130, 16, v131
	v_and_b32_e32 v131, 0xffff0000, v131
	v_pk_mul_f32 v[128:129], v[128:129], v[132:133]
	v_pk_mul_f32 v[136:137], v[136:137], v[138:139]
	v_pk_mul_f32 v[0:1], v[0:1], v[128:129]
	v_lshlrev_b32_e32 v128, 16, v135
	v_and_b32_e32 v129, 0xffff0000, v135
	v_rcp_f32_e32 v128, v128
	v_rcp_f32_e32 v129, v129
	v_pk_mul_f32 v[4:5], v[4:5], v[136:137]
	v_pk_mul_f32 v[128:129], v[128:129], v[130:131]
	s_nop 0
	v_pk_mul_f32 v[2:3], v[2:3], v[128:129]
	s_branch .LBB0_1021

.LBB0_1034:
	s_lshl_b32 s12, s33, 8
	v_mov_b32_e32 v128, v219
	v_mov_b32_e32 v129, v220
	s_or_b32 s12, s12, s35
	s_add_i32 s59, s59, s34
	v_lshl_add_u32 v192, v129, 3, s12
	s_add_i32 s12, s58, 16
	s_ashr_i32 s13, s12, 31
	v_add_u32_e32 v156, s59, v128
	s_lshl_b64 s[12:13], s[12:13], 17
	v_lshlrev_b32_e32 v128, 3, v128
	s_add_u32 s12, s30, s12
	v_lshl_add_u32 v158, v129, 7, v128
	s_addc_u32 s13, s31, s13
	v_add_u32_e32 v128, s38, v158
	v_mov_b32_e32 v129, v193
	v_lshl_add_u64 v[128:129], v[128:129], 1, s[12:13]
	global_load_dwordx4 v[160:163], v[128:129], off
	v_add_u32_e32 v128, s39, v158
	v_mov_b32_e32 v129, v193
	v_lshl_add_u64 v[128:129], v[128:129], 1, s[12:13]
	global_load_dwordx4 v[152:155], v[128:129], off
	v_add_u32_e32 v128, s40, v158
	v_mov_b32_e32 v129, v193
	v_lshl_add_u64 v[128:129], v[128:129], 1, s[12:13]
	global_load_dwordx4 v[148:151], v[128:129], off
	v_add_u32_e32 v128, s42, v158
	v_mov_b32_e32 v129, v193
	v_lshl_add_u64 v[128:129], v[128:129], 1, s[12:13]
	global_load_dwordx4 v[144:147], v[128:129], off
	v_mov_b32_e32 v157, v193
	v_lshlrev_b64 v[164:165], 11, v[156:157]
	v_add_u32_e32 v128, s43, v158
	v_mov_b32_e32 v129, v193
	v_lshl_add_u64 v[128:129], v[128:129], 1, s[12:13]
	global_load_dwordx4 v[140:143], v[128:129], off
	v_add_u32_e32 v128, s44, v158
	v_mov_b32_e32 v129, v193
	v_lshl_add_u64 v[128:129], v[128:129], 1, s[12:13]
	global_load_dwordx4 v[136:139], v[128:129], off
	v_add_u32_e32 v128, s45, v158
	v_mov_b32_e32 v129, v193
	v_lshl_add_u64 v[128:129], v[128:129], 1, s[12:13]
	global_load_dwordx4 v[132:135], v[128:129], off
	v_add_u32_e32 v128, s46, v158
	v_mov_b32_e32 v129, v193
	v_lshl_add_u64 v[128:129], v[128:129], 1, s[12:13]
	global_load_dwordx4 v[128:131], v[128:129], off
	s_and_b64 vcc, exec, s[6:7]
	s_waitcnt vmcnt(7)
	v_lshlrev_b32_e32 v157, 16, v160
	v_rcp_f32_e32 v166, v157
	v_and_b32_e32 v157, 0xffff0000, v160
	v_rcp_f32_e32 v167, v157
	s_nop 0
	v_pk_mul_f32 v[124:125], v[124:125], v[166:167]
	s_nop 0
	v_cvt_pk_bf16_f32 v124, v124, v125
	v_lshlrev_b32_e32 v125, 16, v161
	v_rcp_f32_e32 v160, v125
	v_and_b32_e32 v125, 0xffff0000, v161
	v_rcp_f32_e32 v161, v125
	s_nop 0
	v_pk_mul_f32 v[126:127], v[126:127], v[160:161]
	s_nop 0
	v_cvt_pk_bf16_f32 v125, v126, v127
	v_lshlrev_b32_e32 v126, 16, v162
	v_and_b32_e32 v127, 0xffff0000, v162
	v_rcp_f32_e32 v126, v126
	v_rcp_f32_e32 v127, v127
	s_nop 0
	v_pk_mul_f32 v[120:121], v[120:121], v[126:127]
	s_nop 0
	v_cvt_pk_bf16_f32 v126, v120, v121
	v_lshlrev_b32_e32 v120, 16, v163
	v_and_b32_e32 v121, 0xffff0000, v163
	v_rcp_f32_e32 v120, v120
	v_rcp_f32_e32 v121, v121
	s_nop 0
	v_pk_mul_f32 v[120:121], v[122:123], v[120:121]
	s_nop 0
	v_cvt_pk_bf16_f32 v127, v120, v121
	v_lshl_add_u64 v[122:123], s[2:3], 0, v[164:165]
	v_lshlrev_b64 v[120:121], 1, v[192:193]
	v_lshl_add_u64 v[122:123], v[122:123], 0, v[120:121]
	global_store_dwordx4 v[122:123], v[124:127], off
	v_add_u32_e32 v192, 16, v156
	s_nop 0
	s_waitcnt vmcnt(7)
	v_lshlrev_b32_e32 v124, 16, v152
	v_and_b32_e32 v125, 0xffff0000, v152
	v_rcp_f32_e32 v124, v124
	v_rcp_f32_e32 v125, v125
	s_nop 0
	v_pk_mul_f32 v[116:117], v[116:117], v[124:125]
	s_nop 0
	v_cvt_pk_bf16_f32 v116, v116, v117
	v_lshlrev_b32_e32 v117, 16, v153
	v_rcp_f32_e32 v124, v117
	v_and_b32_e32 v117, 0xffff0000, v153
	v_rcp_f32_e32 v125, v117
	s_nop 0
	v_pk_mul_f32 v[118:119], v[118:119], v[124:125]
	s_nop 0
	v_cvt_pk_bf16_f32 v117, v118, v119
	v_lshlrev_b32_e32 v118, 16, v154
	v_and_b32_e32 v119, 0xffff0000, v154
	v_rcp_f32_e32 v118, v118
	v_rcp_f32_e32 v119, v119
	s_nop 0
	v_pk_mul_f32 v[112:113], v[112:113], v[118:119]
	s_nop 0
	v_cvt_pk_bf16_f32 v118, v112, v113
	v_lshlrev_b32_e32 v112, 16, v155
	v_and_b32_e32 v113, 0xffff0000, v155
	v_rcp_f32_e32 v112, v112
	v_rcp_f32_e32 v113, v113
	s_nop 0
	v_pk_mul_f32 v[112:113], v[114:115], v[112:113]
	s_waitcnt vmcnt(6)
	v_lshlrev_b32_e32 v114, 16, v148
	v_and_b32_e32 v115, 0xffff0000, v148
	v_rcp_f32_e32 v114, v114
	v_rcp_f32_e32 v115, v115
	v_cvt_pk_bf16_f32 v119, v112, v113
	v_lshlrev_b64 v[112:113], 11, v[192:193]
	v_add_u32_e32 v192, 32, v156
	v_pk_mul_f32 v[108:109], v[108:109], v[114:115]
	global_store_dwordx4 v[122:123], v[116:119], off offset:256
	v_cvt_pk_bf16_f32 v108, v108, v109
	v_lshlrev_b32_e32 v109, 16, v149
	v_rcp_f32_e32 v114, v109
	v_and_b32_e32 v109, 0xffff0000, v149
	v_rcp_f32_e32 v115, v109
	s_nop 0
	v_pk_mul_f32 v[110:111], v[110:111], v[114:115]
	s_nop 0
	v_cvt_pk_bf16_f32 v109, v110, v111
	v_lshlrev_b32_e32 v110, 16, v150
	v_and_b32_e32 v111, 0xffff0000, v150
	v_rcp_f32_e32 v110, v110
	v_rcp_f32_e32 v111, v111
	s_nop 0
	v_pk_mul_f32 v[104:105], v[104:105], v[110:111]
	s_nop 0
	v_cvt_pk_bf16_f32 v110, v104, v105
	v_lshlrev_b32_e32 v104, 16, v151
	v_and_b32_e32 v105, 0xffff0000, v151
	v_rcp_f32_e32 v104, v104
	v_rcp_f32_e32 v105, v105
	s_nop 0
	v_pk_mul_f32 v[104:105], v[106:107], v[104:105]
	s_waitcnt vmcnt(6)
	v_lshlrev_b32_e32 v106, 16, v144
	v_and_b32_e32 v107, 0xffff0000, v144
	v_rcp_f32_e32 v106, v106
	v_rcp_f32_e32 v107, v107
	v_cvt_pk_bf16_f32 v111, v104, v105
	v_lshl_add_u64 v[104:105], s[2:3], 0, v[112:113]
	v_lshl_add_u64 v[104:105], v[104:105], 0, v[120:121]
	v_pk_mul_f32 v[100:101], v[100:101], v[106:107]
	global_store_dwordx4 v[104:105], v[108:111], off
	v_cvt_pk_bf16_f32 v100, v100, v101
	v_lshlrev_b32_e32 v101, 16, v145
	v_rcp_f32_e32 v106, v101
	v_and_b32_e32 v101, 0xffff0000, v145
	v_rcp_f32_e32 v107, v101
	s_nop 0
	v_pk_mul_f32 v[102:103], v[102:103], v[106:107]
	s_nop 0
	v_cvt_pk_bf16_f32 v101, v102, v103
	v_lshlrev_b32_e32 v102, 16, v146
	v_and_b32_e32 v103, 0xffff0000, v146
	v_rcp_f32_e32 v102, v102
	v_rcp_f32_e32 v103, v103
	s_nop 0
	v_pk_mul_f32 v[96:97], v[96:97], v[102:103]
	s_nop 0
	v_cvt_pk_bf16_f32 v102, v96, v97
	v_lshlrev_b32_e32 v96, 16, v147
	v_and_b32_e32 v97, 0xffff0000, v147
	v_rcp_f32_e32 v96, v96
	v_rcp_f32_e32 v97, v97
	s_nop 0
	v_pk_mul_f32 v[96:97], v[98:99], v[96:97]
	s_waitcnt vmcnt(6)
	v_lshlrev_b32_e32 v98, 16, v140
	v_and_b32_e32 v99, 0xffff0000, v140
	v_rcp_f32_e32 v98, v98
	v_rcp_f32_e32 v99, v99
	v_cvt_pk_bf16_f32 v103, v96, v97
	v_lshlrev_b64 v[96:97], 11, v[192:193]
	v_add_u32_e32 v192, 48, v156
	v_pk_mul_f32 v[92:93], v[92:93], v[98:99]
	global_store_dwordx4 v[104:105], v[100:103], off offset:256
	v_cvt_pk_bf16_f32 v92, v92, v93
	v_lshlrev_b32_e32 v93, 16, v141
	v_rcp_f32_e32 v98, v93
	v_and_b32_e32 v93, 0xffff0000, v141
	v_rcp_f32_e32 v99, v93
	s_nop 0
	v_pk_mul_f32 v[94:95], v[94:95], v[98:99]
	s_nop 0
	v_cvt_pk_bf16_f32 v93, v94, v95
	v_lshlrev_b32_e32 v94, 16, v142
	v_and_b32_e32 v95, 0xffff0000, v142
	v_rcp_f32_e32 v94, v94
	v_rcp_f32_e32 v95, v95
	s_nop 0
	v_pk_mul_f32 v[88:89], v[88:89], v[94:95]
	s_nop 0
	v_cvt_pk_bf16_f32 v94, v88, v89
	v_lshlrev_b32_e32 v88, 16, v143
	v_and_b32_e32 v89, 0xffff0000, v143
	v_rcp_f32_e32 v88, v88
	v_rcp_f32_e32 v89, v89
	s_nop 0
	v_pk_mul_f32 v[88:89], v[90:91], v[88:89]
	s_waitcnt vmcnt(6)
	v_lshlrev_b32_e32 v90, 16, v136
	v_and_b32_e32 v91, 0xffff0000, v136
	v_rcp_f32_e32 v90, v90
	v_rcp_f32_e32 v91, v91
	v_cvt_pk_bf16_f32 v95, v88, v89
	v_lshl_add_u64 v[88:89], s[2:3], 0, v[96:97]
	v_lshl_add_u64 v[88:89], v[88:89], 0, v[120:121]
	v_pk_mul_f32 v[84:85], v[84:85], v[90:91]
	global_store_dwordx4 v[88:89], v[92:95], off
	v_cvt_pk_bf16_f32 v84, v84, v85
	v_lshlrev_b32_e32 v85, 16, v137
	v_rcp_f32_e32 v90, v85
	v_and_b32_e32 v85, 0xffff0000, v137
	v_rcp_f32_e32 v91, v85
	s_nop 0
	v_pk_mul_f32 v[86:87], v[86:87], v[90:91]
	s_nop 0
	v_cvt_pk_bf16_f32 v85, v86, v87
	v_lshlrev_b32_e32 v86, 16, v138
	v_and_b32_e32 v87, 0xffff0000, v138
	v_rcp_f32_e32 v86, v86
	v_rcp_f32_e32 v87, v87
	s_nop 0
	v_pk_mul_f32 v[80:81], v[80:81], v[86:87]
	s_nop 0
	v_cvt_pk_bf16_f32 v86, v80, v81
	v_lshlrev_b32_e32 v80, 16, v139
	v_and_b32_e32 v81, 0xffff0000, v139
	v_rcp_f32_e32 v80, v80
	v_rcp_f32_e32 v81, v81
	s_nop 0
	v_pk_mul_f32 v[80:81], v[82:83], v[80:81]
	s_waitcnt vmcnt(6)
	v_lshlrev_b32_e32 v82, 16, v132
	v_and_b32_e32 v83, 0xffff0000, v132
	v_rcp_f32_e32 v82, v82
	v_rcp_f32_e32 v83, v83
	v_cvt_pk_bf16_f32 v87, v80, v81
	v_lshlrev_b64 v[80:81], 11, v[192:193]
	v_add_u32_e32 v192, s47, v158
	v_pk_mul_f32 v[76:77], v[76:77], v[82:83]
	global_store_dwordx4 v[88:89], v[84:87], off offset:256
	v_cvt_pk_bf16_f32 v76, v76, v77
	v_lshlrev_b32_e32 v77, 16, v133
	v_rcp_f32_e32 v82, v77
	v_and_b32_e32 v77, 0xffff0000, v133
	v_rcp_f32_e32 v83, v77
	s_nop 0
	v_pk_mul_f32 v[78:79], v[78:79], v[82:83]
	s_nop 0
	v_cvt_pk_bf16_f32 v77, v78, v79
	v_lshlrev_b32_e32 v78, 16, v134
	v_and_b32_e32 v79, 0xffff0000, v134
	v_rcp_f32_e32 v78, v78
	v_rcp_f32_e32 v79, v79
	s_nop 0
	v_pk_mul_f32 v[72:73], v[72:73], v[78:79]
	s_nop 0
	v_cvt_pk_bf16_f32 v78, v72, v73
	v_lshlrev_b32_e32 v72, 16, v135
	v_and_b32_e32 v73, 0xffff0000, v135
	v_rcp_f32_e32 v72, v72
	v_rcp_f32_e32 v73, v73
	s_nop 0
	v_pk_mul_f32 v[72:73], v[74:75], v[72:73]
	s_waitcnt vmcnt(6)
	v_lshlrev_b32_e32 v74, 16, v128
	v_and_b32_e32 v75, 0xffff0000, v128
	v_rcp_f32_e32 v74, v74
	v_rcp_f32_e32 v75, v75
	v_cvt_pk_bf16_f32 v79, v72, v73
	v_lshl_add_u64 v[72:73], s[2:3], 0, v[80:81]
	v_lshl_add_u64 v[72:73], v[72:73], 0, v[120:121]
	v_pk_mul_f32 v[68:69], v[68:69], v[74:75]
	global_store_dwordx4 v[72:73], v[76:79], off
	v_cvt_pk_bf16_f32 v68, v68, v69
	v_lshlrev_b32_e32 v69, 16, v129
	v_rcp_f32_e32 v74, v69
	v_and_b32_e32 v69, 0xffff0000, v129
	v_rcp_f32_e32 v75, v69
	s_nop 0
	v_pk_mul_f32 v[70:71], v[70:71], v[74:75]
	s_nop 0
	v_cvt_pk_bf16_f32 v69, v70, v71
	v_lshlrev_b32_e32 v70, 16, v130
	v_and_b32_e32 v71, 0xffff0000, v130
	v_rcp_f32_e32 v70, v70
	v_rcp_f32_e32 v71, v71
	s_nop 0
	v_pk_mul_f32 v[64:65], v[64:65], v[70:71]
	s_nop 0
	v_cvt_pk_bf16_f32 v70, v64, v65
	v_lshlrev_b32_e32 v64, 16, v131
	v_and_b32_e32 v65, 0xffff0000, v131
	v_rcp_f32_e32 v64, v64
	v_rcp_f32_e32 v65, v65
	s_nop 0
	v_pk_mul_f32 v[64:65], v[66:67], v[64:65]
	s_nop 0
	v_cvt_pk_bf16_f32 v71, v64, v65
	global_store_dwordx4 v[72:73], v[68:71], off offset:256
	v_lshl_add_u64 v[64:65], v[192:193], 1, s[12:13]
	global_load_dwordx4 v[88:91], v[64:65], off
	v_add_u32_e32 v192, s48, v158
	v_lshl_add_u64 v[64:65], v[192:193], 1, s[12:13]
	global_load_dwordx4 v[92:95], v[64:65], off
	v_add_u32_e32 v192, s49, v158
	v_lshl_add_u64 v[64:65], v[192:193], 1, s[12:13]
	global_load_dwordx4 v[84:87], v[64:65], off
	v_add_u32_e32 v192, s50, v158
	v_lshl_add_u64 v[64:65], v[192:193], 1, s[12:13]
	global_load_dwordx4 v[80:83], v[64:65], off
	v_add_u32_e32 v192, s51, v158
	v_lshl_add_u64 v[64:65], v[192:193], 1, s[12:13]
	global_load_dwordx4 v[76:79], v[64:65], off
	v_add_u32_e32 v192, s52, v158
	v_lshl_add_u64 v[64:65], v[192:193], 1, s[12:13]
	global_load_dwordx4 v[72:75], v[64:65], off
	v_add_u32_e32 v192, s53, v158
	v_lshl_add_u64 v[64:65], v[192:193], 1, s[12:13]
	global_load_dwordx4 v[68:71], v[64:65], off
	v_add_u32_e32 v192, s54, v158
	v_lshl_add_u64 v[64:65], v[192:193], 1, s[12:13]
	global_load_dwordx4 v[64:67], v[64:65], off
	v_add_u32_e32 v192, 0x80, v156
	v_lshlrev_b64 v[96:97], 11, v[192:193]
	v_add_u32_e32 v192, 0x90, v156
	s_mov_b64 s[12:13], -1
	s_waitcnt vmcnt(7)
	v_lshlrev_b32_e32 v98, 16, v88
	v_and_b32_e32 v88, 0xffff0000, v88
	v_rcp_f32_e32 v98, v98
	v_rcp_f32_e32 v99, v88
	s_nop 0
	v_pk_mul_f32 v[60:61], v[60:61], v[98:99]
	s_nop 0
	v_cvt_pk_bf16_f32 v60, v60, v61
	v_lshlrev_b32_e32 v61, 16, v89
	v_rcp_f32_e32 v88, v61
	v_and_b32_e32 v61, 0xffff0000, v89
	v_rcp_f32_e32 v89, v61
	s_nop 0
	v_pk_mul_f32 v[62:63], v[62:63], v[88:89]
	s_nop 0
	v_cvt_pk_bf16_f32 v61, v62, v63
	v_lshlrev_b32_e32 v62, 16, v90
	v_and_b32_e32 v63, 0xffff0000, v90
	v_rcp_f32_e32 v62, v62
	v_rcp_f32_e32 v63, v63
	s_nop 0
	v_pk_mul_f32 v[56:57], v[56:57], v[62:63]
	s_nop 0
	v_cvt_pk_bf16_f32 v62, v56, v57
	v_lshlrev_b32_e32 v56, 16, v91
	v_and_b32_e32 v57, 0xffff0000, v91
	v_rcp_f32_e32 v56, v56
	v_rcp_f32_e32 v57, v57
	s_nop 0
	v_pk_mul_f32 v[56:57], v[58:59], v[56:57]
	s_waitcnt vmcnt(6)
	v_lshlrev_b32_e32 v58, 16, v92
	v_and_b32_e32 v59, 0xffff0000, v92
	v_rcp_f32_e32 v58, v58
	v_rcp_f32_e32 v59, v59
	v_cvt_pk_bf16_f32 v63, v56, v57
	v_lshl_add_u64 v[56:57], s[2:3], 0, v[96:97]
	v_lshl_add_u64 v[56:57], v[56:57], 0, v[120:121]
	v_pk_mul_f32 v[52:53], v[52:53], v[58:59]
	global_store_dwordx4 v[56:57], v[60:63], off
	v_cvt_pk_bf16_f32 v52, v52, v53
	v_lshlrev_b32_e32 v53, 16, v93
	v_rcp_f32_e32 v58, v53
	v_and_b32_e32 v53, 0xffff0000, v93
	v_rcp_f32_e32 v59, v53
	s_nop 0
	v_pk_mul_f32 v[54:55], v[54:55], v[58:59]
	s_nop 0
	v_cvt_pk_bf16_f32 v53, v54, v55
	v_lshlrev_b32_e32 v54, 16, v94
	v_and_b32_e32 v55, 0xffff0000, v94
	v_rcp_f32_e32 v54, v54
	v_rcp_f32_e32 v55, v55
	s_nop 0
	v_pk_mul_f32 v[48:49], v[48:49], v[54:55]
	s_nop 0
	v_cvt_pk_bf16_f32 v54, v48, v49
	v_lshlrev_b32_e32 v48, 16, v95
	v_and_b32_e32 v49, 0xffff0000, v95
	v_rcp_f32_e32 v48, v48
	v_rcp_f32_e32 v49, v49
	s_nop 0
	v_pk_mul_f32 v[48:49], v[50:51], v[48:49]
	s_waitcnt vmcnt(6)
	v_lshlrev_b32_e32 v50, 16, v84
	v_and_b32_e32 v51, 0xffff0000, v84
	v_rcp_f32_e32 v50, v50
	v_rcp_f32_e32 v51, v51
	v_cvt_pk_bf16_f32 v55, v48, v49
	v_lshlrev_b64 v[48:49], 11, v[192:193]
	v_add_u32_e32 v192, 0xa0, v156
	v_pk_mul_f32 v[44:45], v[44:45], v[50:51]
	global_store_dwordx4 v[56:57], v[52:55], off offset:256
	v_cvt_pk_bf16_f32 v44, v44, v45
	v_lshlrev_b32_e32 v45, 16, v85
	v_rcp_f32_e32 v50, v45
	v_and_b32_e32 v45, 0xffff0000, v85
	v_rcp_f32_e32 v51, v45
	s_nop 0
	v_pk_mul_f32 v[46:47], v[46:47], v[50:51]
	s_nop 0
	v_cvt_pk_bf16_f32 v45, v46, v47
	v_lshlrev_b32_e32 v46, 16, v86
	v_and_b32_e32 v47, 0xffff0000, v86
	v_rcp_f32_e32 v46, v46
	v_rcp_f32_e32 v47, v47
	s_nop 0
	v_pk_mul_f32 v[40:41], v[40:41], v[46:47]
	s_nop 0
	v_cvt_pk_bf16_f32 v46, v40, v41
	v_lshlrev_b32_e32 v40, 16, v87
	v_and_b32_e32 v41, 0xffff0000, v87
	v_rcp_f32_e32 v40, v40
	v_rcp_f32_e32 v41, v41
	s_nop 0
	v_pk_mul_f32 v[40:41], v[42:43], v[40:41]
	s_waitcnt vmcnt(6)
	v_lshlrev_b32_e32 v42, 16, v80
	v_and_b32_e32 v43, 0xffff0000, v80
	v_rcp_f32_e32 v42, v42
	v_rcp_f32_e32 v43, v43
	v_cvt_pk_bf16_f32 v47, v40, v41
	v_lshl_add_u64 v[40:41], s[2:3], 0, v[48:49]
	v_lshl_add_u64 v[40:41], v[40:41], 0, v[120:121]
	v_pk_mul_f32 v[36:37], v[36:37], v[42:43]
	global_store_dwordx4 v[40:41], v[44:47], off
	v_cvt_pk_bf16_f32 v36, v36, v37
	v_lshlrev_b32_e32 v37, 16, v81
	v_rcp_f32_e32 v42, v37
	v_and_b32_e32 v37, 0xffff0000, v81
	v_rcp_f32_e32 v43, v37
	s_nop 0
	v_pk_mul_f32 v[38:39], v[38:39], v[42:43]
	s_nop 0
	v_cvt_pk_bf16_f32 v37, v38, v39
	v_lshlrev_b32_e32 v38, 16, v82
	v_and_b32_e32 v39, 0xffff0000, v82
	v_rcp_f32_e32 v38, v38
	v_rcp_f32_e32 v39, v39
	s_nop 0
	v_pk_mul_f32 v[32:33], v[32:33], v[38:39]
	s_nop 0
	v_cvt_pk_bf16_f32 v38, v32, v33
	v_lshlrev_b32_e32 v32, 16, v83
	v_and_b32_e32 v33, 0xffff0000, v83
	v_rcp_f32_e32 v32, v32
	v_rcp_f32_e32 v33, v33
	s_nop 0
	v_pk_mul_f32 v[32:33], v[34:35], v[32:33]
	s_waitcnt vmcnt(6)
	v_lshlrev_b32_e32 v34, 16, v76
	v_and_b32_e32 v35, 0xffff0000, v76
	v_rcp_f32_e32 v34, v34
	v_rcp_f32_e32 v35, v35
	v_cvt_pk_bf16_f32 v39, v32, v33
	v_lshlrev_b64 v[32:33], 11, v[192:193]
	v_add_u32_e32 v192, 0xb0, v156
	v_pk_mul_f32 v[28:29], v[28:29], v[34:35]
	global_store_dwordx4 v[40:41], v[36:39], off offset:256
	v_cvt_pk_bf16_f32 v28, v28, v29
	v_lshlrev_b32_e32 v29, 16, v77
	v_rcp_f32_e32 v34, v29
	v_and_b32_e32 v29, 0xffff0000, v77
	v_rcp_f32_e32 v35, v29
	s_nop 0
	v_pk_mul_f32 v[30:31], v[30:31], v[34:35]
	s_nop 0
	v_cvt_pk_bf16_f32 v29, v30, v31
	v_lshlrev_b32_e32 v30, 16, v78
	v_and_b32_e32 v31, 0xffff0000, v78
	v_rcp_f32_e32 v30, v30
	v_rcp_f32_e32 v31, v31
	s_nop 0
	v_pk_mul_f32 v[24:25], v[24:25], v[30:31]
	s_nop 0
	v_cvt_pk_bf16_f32 v30, v24, v25
	v_lshlrev_b32_e32 v24, 16, v79
	v_and_b32_e32 v25, 0xffff0000, v79
	v_rcp_f32_e32 v24, v24
	v_rcp_f32_e32 v25, v25
	s_nop 0
	v_pk_mul_f32 v[24:25], v[26:27], v[24:25]
	s_waitcnt vmcnt(6)
	v_lshlrev_b32_e32 v26, 16, v72
	v_and_b32_e32 v27, 0xffff0000, v72
	v_rcp_f32_e32 v26, v26
	v_rcp_f32_e32 v27, v27
	v_cvt_pk_bf16_f32 v31, v24, v25
	v_lshl_add_u64 v[24:25], s[2:3], 0, v[32:33]
	v_lshl_add_u64 v[24:25], v[24:25], 0, v[120:121]
	v_pk_mul_f32 v[20:21], v[20:21], v[26:27]
	global_store_dwordx4 v[24:25], v[28:31], off
	v_cvt_pk_bf16_f32 v20, v20, v21
	v_lshlrev_b32_e32 v21, 16, v73
	v_rcp_f32_e32 v26, v21
	v_and_b32_e32 v21, 0xffff0000, v73
	v_rcp_f32_e32 v27, v21
	s_nop 0
	v_pk_mul_f32 v[22:23], v[22:23], v[26:27]
	s_nop 0
	v_cvt_pk_bf16_f32 v21, v22, v23
	v_lshlrev_b32_e32 v22, 16, v74
	v_and_b32_e32 v23, 0xffff0000, v74
	v_rcp_f32_e32 v22, v22
	v_rcp_f32_e32 v23, v23
	s_nop 0
	v_pk_mul_f32 v[16:17], v[16:17], v[22:23]
	s_nop 0
	v_cvt_pk_bf16_f32 v22, v16, v17
	v_lshlrev_b32_e32 v16, 16, v75
	v_and_b32_e32 v17, 0xffff0000, v75
	v_rcp_f32_e32 v16, v16
	v_rcp_f32_e32 v17, v17
	s_nop 0
	v_pk_mul_f32 v[16:17], v[18:19], v[16:17]
	s_waitcnt vmcnt(6)
	v_lshlrev_b32_e32 v18, 16, v68
	v_and_b32_e32 v19, 0xffff0000, v68
	v_rcp_f32_e32 v18, v18
	v_rcp_f32_e32 v19, v19
	v_cvt_pk_bf16_f32 v23, v16, v17
	v_lshlrev_b64 v[16:17], 11, v[192:193]
	global_store_dwordx4 v[24:25], v[20:23], off offset:256
	v_pk_mul_f32 v[12:13], v[12:13], v[18:19]
	s_nop 0
	v_cvt_pk_bf16_f32 v12, v12, v13
	v_lshlrev_b32_e32 v13, 16, v69
	v_rcp_f32_e32 v18, v13
	v_and_b32_e32 v13, 0xffff0000, v69
	v_rcp_f32_e32 v19, v13
	s_nop 0
	v_pk_mul_f32 v[14:15], v[14:15], v[18:19]
	s_nop 0
	v_cvt_pk_bf16_f32 v13, v14, v15
	v_lshlrev_b32_e32 v14, 16, v70
	v_and_b32_e32 v15, 0xffff0000, v70
	v_rcp_f32_e32 v14, v14
	v_rcp_f32_e32 v15, v15
	s_nop 0
	v_pk_mul_f32 v[8:9], v[8:9], v[14:15]
	s_nop 0
	v_cvt_pk_bf16_f32 v14, v8, v9
	v_lshlrev_b32_e32 v8, 16, v71
	v_and_b32_e32 v9, 0xffff0000, v71
	v_rcp_f32_e32 v8, v8
	v_rcp_f32_e32 v9, v9
	s_nop 0
	v_pk_mul_f32 v[8:9], v[10:11], v[8:9]
	s_waitcnt vmcnt(6)
	v_lshlrev_b32_e32 v10, 16, v64
	v_and_b32_e32 v11, 0xffff0000, v64
	v_rcp_f32_e32 v10, v10
	v_rcp_f32_e32 v11, v11
	v_cvt_pk_bf16_f32 v15, v8, v9
	v_lshl_add_u64 v[8:9], s[2:3], 0, v[16:17]
	v_lshl_add_u64 v[8:9], v[8:9], 0, v[120:121]
	v_pk_mul_f32 v[4:5], v[4:5], v[10:11]
	global_store_dwordx4 v[8:9], v[12:15], off
	v_cvt_pk_bf16_f32 v4, v4, v5
	v_lshlrev_b32_e32 v5, 16, v65
	v_rcp_f32_e32 v10, v5
	v_and_b32_e32 v5, 0xffff0000, v65
	v_rcp_f32_e32 v11, v5
	s_nop 0
	v_pk_mul_f32 v[6:7], v[6:7], v[10:11]
	s_nop 0
	v_cvt_pk_bf16_f32 v5, v6, v7
	v_lshlrev_b32_e32 v6, 16, v66
	v_and_b32_e32 v7, 0xffff0000, v66
	v_rcp_f32_e32 v6, v6
	v_rcp_f32_e32 v7, v7
	s_nop 0
	v_pk_mul_f32 v[0:1], v[0:1], v[6:7]
	s_nop 0
	v_cvt_pk_bf16_f32 v6, v0, v1
	v_lshlrev_b32_e32 v0, 16, v67
	v_and_b32_e32 v1, 0xffff0000, v67
	v_rcp_f32_e32 v0, v0
	v_rcp_f32_e32 v1, v1
	s_nop 0
	v_pk_mul_f32 v[0:1], v[2:3], v[0:1]
	s_nop 0
	v_cvt_pk_bf16_f32 v7, v0, v1
	global_store_dwordx4 v[8:9], v[4:7], off offset:256
	s_cbranch_vccnz .LBB0_1011
	s_andn2_b64 vcc, exec, s[0:1]
	s_cbranch_vccnz .LBB0_1010
	s_barrier
	s_branch .LBB0_1010
